# vAA with sc1 kept on the PROJ stores but removed from the 12 EpiUpConv G/EXA/EXB stores (which group carries the write-through benefit)
# baseline (speedup 1.0000x reference)
.LBB0_777:
	s_or_b64 exec, exec, s[44:45]
	v_lshlrev_b64 v[150:151], 1, v[192:193]
	v_lshl_add_u64 v[152:153], v[220:221], 0, v[150:151]
	s_waitcnt lgkmcnt(0)
	v_pk_mul_f32 v[108:109], v[108:109], v[214:215] op_sel_hi:[1,0]
	global_store_dwordx4 v[152:153], v[144:147], off
	ds_bpermute_b32 v144, v173, v108
	ds_bpermute_b32 v145, v175, v108
	v_cmp_eq_u32_e64 s[46:47], 0, v176
	s_waitcnt vmcnt(2)
	v_fma_f32 v108, v140, v108, v128
	ds_bpermute_b32 v146, v173, v109
	s_waitcnt lgkmcnt(2)
	v_cndmask_b32_e64 v158, v144, v225, s[46:47]
	s_waitcnt lgkmcnt(1)
	v_cndmask_b32_e32 v159, v145, v224, vcc
	v_fmac_f32_e32 v108, v136, v158
	ds_bpermute_b32 v147, v175, v109
	v_fmac_f32_e32 v108, v132, v159
	v_mul_f32_e32 v158, 0xbfb8aa3b, v108
	v_exp_f32_e32 v158, v158
	v_pk_mul_f32 v[110:111], v[110:111], v[214:215] op_sel_hi:[1,0]
	ds_bpermute_b32 v153, v173, v110
	s_waitcnt lgkmcnt(2)
	v_cndmask_b32_e64 v159, v146, v222, s[46:47]
	v_fma_f32 v109, v141, v109, v129
	ds_bpermute_b32 v152, v173, v111
	ds_bpermute_b32 v154, v175, v110
	s_waitcnt lgkmcnt(3)
	v_cndmask_b32_e32 v179, v147, v215, vcc
	v_fmac_f32_e32 v109, v137, v159
	ds_bpermute_b32 v155, v175, v111
	v_add_f32_e32 v158, 1.0, v158
	v_fmac_f32_e32 v109, v133, v179
	v_rcp_f32_e32 v158, v158
	v_mul_f32_e32 v159, 0xbfb8aa3b, v109
	v_exp_f32_e32 v159, v159
	s_waitcnt lgkmcnt(3)
	v_cndmask_b32_e64 v157, v153, v226, s[46:47]
	v_fma_f32 v110, v142, v110, v130
	s_waitcnt lgkmcnt(2)
	v_cndmask_b32_e64 v156, v152, v227, s[46:47]
	s_waitcnt lgkmcnt(1)
	v_cndmask_b32_e32 v179, v154, v213, vcc
	v_fmac_f32_e32 v110, v138, v157
	v_fma_f32 v111, v143, v111, v131
	v_pk_mul_f32 v[104:105], v[104:105], v[214:215] op_sel_hi:[1,0]
	s_waitcnt lgkmcnt(0)
	v_cndmask_b32_e32 v178, v155, v223, vcc
	v_mul_f32_e32 v108, v108, v158
	v_fmac_f32_e32 v110, v134, v179
	v_fmac_f32_e32 v111, v139, v156
	v_mul_f32_e32 v104, v104, v108
	v_add_f32_e32 v108, 1.0, v159
	v_mul_f32_e32 v157, 0xbfb8aa3b, v110
	v_fmac_f32_e32 v111, v135, v178
	v_rcp_f32_e32 v108, v108
	v_exp_f32_e32 v157, v157
	v_mul_f32_e32 v156, 0xbfb8aa3b, v111
	v_exp_f32_e32 v156, v156
	v_pk_mul_f32 v[102:103], v[102:103], v[214:215] op_sel_hi:[1,0]
	v_mul_f32_e32 v108, v109, v108
	v_add_f32_e32 v109, 1.0, v157
	ds_bpermute_b32 v157, v173, v103
	v_rcp_f32_e32 v109, v109
	v_add_f32_e32 v156, 1.0, v156
	ds_bpermute_b32 v158, v175, v103
	v_rcp_f32_e32 v156, v156
	v_pk_mul_f32 v[106:107], v[106:107], v[214:215] op_sel_hi:[1,0]
	v_mul_f32_e32 v105, v105, v108
	v_mul_f32_e32 v108, v110, v109
	s_waitcnt lgkmcnt(1)
	v_cndmask_b32_e64 v180, v157, v211, s[46:47]
	v_fma_f32 v103, v127, v103, v115
	v_mul_f32_e32 v106, v106, v108
	v_mul_f32_e32 v108, v111, v156
	ds_bpermute_b32 v156, v173, v102
	s_waitcnt lgkmcnt(1)
	v_cndmask_b32_e32 v181, v158, v209, vcc
	v_fmac_f32_e32 v103, v123, v180
	ds_bpermute_b32 v159, v175, v102
	v_fmac_f32_e32 v103, v119, v181
	v_mul_f32_e32 v180, 0xbfb8aa3b, v103
	v_exp_f32_e32 v180, v180
	v_pk_mul_f32 v[100:101], v[100:101], v[214:215] op_sel_hi:[1,0]
	ds_bpermute_b32 v110, v173, v101
	s_waitcnt lgkmcnt(2)
	v_cndmask_b32_e64 v181, v156, v197, s[46:47]
	v_fma_f32 v102, v126, v102, v114
	v_mul_f32_e32 v107, v107, v108
	ds_bpermute_b32 v108, v173, v100
	ds_bpermute_b32 v111, v175, v101
	s_waitcnt lgkmcnt(3)
	v_cndmask_b32_e32 v182, v159, v201, vcc
	v_fmac_f32_e32 v102, v122, v181
	ds_bpermute_b32 v109, v175, v100
	v_add_f32_e32 v180, 1.0, v180
	v_fmac_f32_e32 v102, v118, v182
	v_rcp_f32_e32 v180, v180
	v_mul_f32_e32 v181, 0xbfb8aa3b, v102
	v_exp_f32_e32 v181, v181
	s_waitcnt lgkmcnt(3)
	v_cndmask_b32_e64 v179, v110, v205, s[46:47]
	v_fma_f32 v101, v125, v101, v113
	s_waitcnt lgkmcnt(2)
	v_cndmask_b32_e64 v178, v108, v203, s[46:47]
	s_waitcnt lgkmcnt(1)
	v_cndmask_b32_e32 v182, v111, v191, vcc
	v_fmac_f32_e32 v101, v121, v179
	v_fma_f32 v100, v124, v100, v112
	v_pk_mul_f32 v[98:99], v[98:99], v[214:215] op_sel_hi:[1,0]
	s_waitcnt lgkmcnt(0)
	v_cndmask_b32_e32 v183, v109, v195, vcc
	v_mul_f32_e32 v103, v103, v180
	v_fmac_f32_e32 v101, v117, v182
	v_fmac_f32_e32 v100, v120, v178
	v_mul_f32_e32 v103, v99, v103
	v_add_f32_e32 v99, 1.0, v181
	v_mul_f32_e32 v179, 0xbfb8aa3b, v101
	v_fmac_f32_e32 v100, v116, v183
	v_rcp_f32_e32 v99, v99
	v_exp_f32_e32 v179, v179
	v_mul_f32_e32 v178, 0xbfb8aa3b, v100
	v_exp_f32_e32 v178, v178
	v_mul_f32_e32 v99, v102, v99
	v_add_f32_e32 v102, 1.0, v179
	v_rcp_f32_e32 v102, v102
	v_add_f32_e32 v178, 1.0, v178
	v_rcp_f32_e32 v178, v178
	v_pk_mul_f32 v[96:97], v[96:97], v[214:215] op_sel_hi:[1,0]
	v_mul_f32_e32 v179, v98, v99
	v_mul_f32_e32 v98, v101, v102
	v_mul_f32_e32 v97, v97, v98
	v_mul_f32_e32 v98, v100, v178
	v_mul_f32_e32 v96, v96, v98
	v_cvt_pk_bf16_f32 v98, v104, v105
	v_cvt_pk_bf16_f32 v99, v106, v107
	v_cvt_pk_bf16_f32 v100, v96, v97
	v_mov_b64_e32 v[96:97], s[52:53]
	v_cvt_pk_bf16_f32 v101, v179, v103
	v_mad_i64_i32 v[102:103], s[6:7], v204, s25, v[96:97]
	v_lshl_add_u64 v[102:103], v[102:103], 0, v[150:151]
	v_pk_mul_f32 v[92:93], v[92:93], v[212:213] op_sel_hi:[1,0]
	global_store_dwordx4 v[102:103], v[98:101], off
	ds_bpermute_b32 v98, v173, v92
	ds_bpermute_b32 v99, v175, v92
	v_fma_f32 v92, v140, v92, v128
	ds_bpermute_b32 v100, v173, v93
	ds_bpermute_b32 v103, v175, v93
	s_waitcnt lgkmcnt(3)
	v_cndmask_b32_e64 v144, v98, v144, s[46:47]
	s_waitcnt lgkmcnt(2)
	v_cndmask_b32_e32 v145, v99, v145, vcc
	v_fmac_f32_e32 v92, v136, v144
	v_fmac_f32_e32 v92, v132, v145
	v_mul_f32_e32 v144, 0xbfb8aa3b, v92
	v_exp_f32_e32 v144, v144
	v_pk_mul_f32 v[94:95], v[94:95], v[212:213] op_sel_hi:[1,0]
	ds_bpermute_b32 v102, v173, v94
	s_waitcnt lgkmcnt(2)
	v_cndmask_b32_e64 v145, v100, v146, s[46:47]
	v_fma_f32 v93, v141, v93, v129
	ds_bpermute_b32 v101, v173, v95
	ds_bpermute_b32 v104, v175, v94
	s_waitcnt lgkmcnt(3)
	v_cndmask_b32_e32 v147, v103, v147, vcc
	v_fmac_f32_e32 v93, v137, v145
	ds_bpermute_b32 v105, v175, v95
	v_add_f32_e32 v144, 1.0, v144
	v_fmac_f32_e32 v93, v133, v147
	v_rcp_f32_e32 v144, v144
	v_mul_f32_e32 v145, 0xbfb8aa3b, v93
	v_exp_f32_e32 v145, v145
	s_waitcnt lgkmcnt(3)
	v_cndmask_b32_e64 v107, v102, v153, s[46:47]
	v_fma_f32 v94, v142, v94, v130
	s_waitcnt lgkmcnt(2)
	v_cndmask_b32_e64 v106, v101, v152, s[46:47]
	s_waitcnt lgkmcnt(1)
	v_cndmask_b32_e32 v147, v104, v154, vcc
	v_fmac_f32_e32 v94, v138, v107
	v_fma_f32 v95, v143, v95, v131
	v_pk_mul_f32 v[88:89], v[88:89], v[212:213] op_sel_hi:[1,0]
	s_waitcnt lgkmcnt(0)
	v_cndmask_b32_e32 v146, v105, v155, vcc
	v_mul_f32_e32 v92, v92, v144
	v_fmac_f32_e32 v94, v134, v147
	v_fmac_f32_e32 v95, v139, v106
	v_mul_f32_e32 v88, v88, v92
	v_add_f32_e32 v92, 1.0, v145
	v_mul_f32_e32 v107, 0xbfb8aa3b, v94
	v_fmac_f32_e32 v95, v135, v146
	v_rcp_f32_e32 v92, v92
	v_exp_f32_e32 v107, v107
	v_mul_f32_e32 v106, 0xbfb8aa3b, v95
	v_exp_f32_e32 v106, v106
	v_pk_mul_f32 v[86:87], v[86:87], v[212:213] op_sel_hi:[1,0]
	v_mul_f32_e32 v92, v93, v92
	v_add_f32_e32 v93, 1.0, v107
	ds_bpermute_b32 v107, v173, v87
	v_rcp_f32_e32 v93, v93
	v_add_f32_e32 v106, 1.0, v106
	ds_bpermute_b32 v144, v175, v87
	v_rcp_f32_e32 v106, v106
	v_pk_mul_f32 v[90:91], v[90:91], v[212:213] op_sel_hi:[1,0]
	v_mul_f32_e32 v89, v89, v92
	v_mul_f32_e32 v92, v94, v93
	s_waitcnt lgkmcnt(1)
	v_cndmask_b32_e64 v146, v107, v157, s[46:47]
	v_fma_f32 v87, v127, v87, v115
	v_mul_f32_e32 v90, v90, v92
	v_mul_f32_e32 v92, v95, v106
	ds_bpermute_b32 v106, v173, v86
	s_waitcnt lgkmcnt(1)
	v_cndmask_b32_e32 v147, v144, v158, vcc
	v_fmac_f32_e32 v87, v123, v146
	ds_bpermute_b32 v145, v175, v86
	v_fmac_f32_e32 v87, v119, v147
	v_mul_f32_e32 v146, 0xbfb8aa3b, v87
	v_exp_f32_e32 v146, v146
	v_pk_mul_f32 v[84:85], v[84:85], v[212:213] op_sel_hi:[1,0]
	ds_bpermute_b32 v94, v173, v85
	s_waitcnt lgkmcnt(2)
	v_cndmask_b32_e64 v147, v106, v156, s[46:47]
	v_fma_f32 v86, v126, v86, v114
	v_mul_f32_e32 v91, v91, v92
	ds_bpermute_b32 v92, v173, v84
	ds_bpermute_b32 v95, v175, v85
	s_waitcnt lgkmcnt(3)
	v_cndmask_b32_e32 v152, v145, v159, vcc
	v_fmac_f32_e32 v86, v122, v147
	ds_bpermute_b32 v93, v175, v84
	v_add_f32_e32 v146, 1.0, v146
	v_fmac_f32_e32 v86, v118, v152
	v_rcp_f32_e32 v146, v146
	v_mul_f32_e32 v147, 0xbfb8aa3b, v86
	v_exp_f32_e32 v147, v147
	s_waitcnt lgkmcnt(3)
	v_cndmask_b32_e64 v110, v94, v110, s[46:47]
	v_fma_f32 v85, v125, v85, v113
	s_waitcnt lgkmcnt(2)
	v_cndmask_b32_e64 v108, v92, v108, s[46:47]
	s_waitcnt lgkmcnt(1)
	v_cndmask_b32_e32 v111, v95, v111, vcc
	v_fmac_f32_e32 v85, v121, v110
	v_fma_f32 v84, v124, v84, v112
	v_pk_mul_f32 v[82:83], v[82:83], v[212:213] op_sel_hi:[1,0]
	s_waitcnt lgkmcnt(0)
	v_cndmask_b32_e32 v109, v93, v109, vcc
	v_mul_f32_e32 v87, v87, v146
	v_fmac_f32_e32 v85, v117, v111
	v_fmac_f32_e32 v84, v120, v108
	v_mul_f32_e32 v83, v83, v87
	v_add_f32_e32 v87, 1.0, v147
	v_mul_f32_e32 v110, 0xbfb8aa3b, v85
	v_fmac_f32_e32 v84, v116, v109
	v_rcp_f32_e32 v87, v87
	v_exp_f32_e32 v110, v110
	v_mul_f32_e32 v108, 0xbfb8aa3b, v84
	v_exp_f32_e32 v108, v108
	v_mul_f32_e32 v86, v86, v87
	v_add_f32_e32 v87, 1.0, v110
	v_rcp_f32_e32 v87, v87
	v_add_f32_e32 v108, 1.0, v108
	v_rcp_f32_e32 v108, v108
	v_pk_mul_f32 v[80:81], v[80:81], v[212:213] op_sel_hi:[1,0]
	v_mul_f32_e32 v86, v82, v86
	v_mul_f32_e32 v82, v85, v87
	v_mul_f32_e32 v82, v81, v82
	v_mul_f32_e32 v81, v84, v108
	v_mul_f32_e32 v84, v80, v81
	v_cvt_pk_bf16_f32 v80, v88, v89
	v_cvt_pk_bf16_f32 v81, v90, v91
	v_cvt_pk_bf16_f32 v82, v84, v82
	v_mad_i64_i32 v[84:85], s[6:7], v200, s25, v[96:97]
	v_lshl_add_u64 v[84:85], v[84:85], 0, v[150:151]
	v_pk_mul_f32 v[76:77], v[76:77], v[210:211] op_sel_hi:[1,0]
	v_cvt_pk_bf16_f32 v83, v86, v83
	global_store_dwordx4 v[84:85], v[80:83], off
	ds_bpermute_b32 v80, v173, v76
	ds_bpermute_b32 v81, v175, v76
	v_pk_mul_f32 v[78:79], v[78:79], v[210:211] op_sel_hi:[1,0]
	v_fma_f32 v88, v140, v76, v128
	ds_bpermute_b32 v82, v173, v77
	s_waitcnt lgkmcnt(2)
	v_cndmask_b32_e64 v80, v80, v98, s[46:47]
	ds_bpermute_b32 v87, v175, v79
	s_waitcnt lgkmcnt(2)
	v_cndmask_b32_e32 v81, v81, v99, vcc
	v_fmac_f32_e32 v88, v136, v80
	ds_bpermute_b32 v85, v175, v77
	v_fmac_f32_e32 v88, v132, v81
	v_mul_f32_e32 v80, 0xbfb8aa3b, v88
	v_exp_f32_e32 v80, v80
	s_waitcnt lgkmcnt(2)
	v_cndmask_b32_e64 v81, v82, v100, s[46:47]
	s_waitcnt lgkmcnt(1)
	v_cndmask_b32_e32 v82, v87, v105, vcc
	v_fma_f32 v87, v141, v77, v129
	s_waitcnt lgkmcnt(0)
	v_cndmask_b32_e32 v85, v85, v103, vcc
	v_fmac_f32_e32 v87, v137, v81
	v_add_f32_e32 v80, 1.0, v80
	v_fmac_f32_e32 v87, v133, v85
	ds_bpermute_b32 v84, v173, v78
	v_rcp_f32_e32 v80, v80
	v_mul_f32_e32 v81, 0xbfb8aa3b, v87
	ds_bpermute_b32 v86, v175, v78
	v_exp_f32_e32 v81, v81
	ds_bpermute_b32 v83, v173, v79
	v_pk_mul_f32 v[72:73], v[72:73], v[210:211] op_sel_hi:[1,0]
	v_mul_f32_e32 v80, v88, v80
	s_waitcnt lgkmcnt(2)
	v_cndmask_b32_e64 v84, v84, v102, s[46:47]
	v_mul_f32_e32 v72, v72, v80
	v_add_f32_e32 v80, 1.0, v81
	v_fma_f32 v81, v142, v78, v130
	s_waitcnt lgkmcnt(1)
	v_cndmask_b32_e32 v85, v86, v104, vcc
	v_fmac_f32_e32 v81, v138, v84
	s_waitcnt lgkmcnt(0)
	v_cndmask_b32_e64 v83, v83, v101, s[46:47]
	v_fmac_f32_e32 v81, v134, v85
	v_fma_f32 v85, v143, v79, v131
	v_fmac_f32_e32 v85, v139, v83
	v_mul_f32_e32 v84, 0xbfb8aa3b, v81
	v_fmac_f32_e32 v85, v135, v82
	v_exp_f32_e32 v84, v84
	v_mul_f32_e32 v82, 0xbfb8aa3b, v85
	v_exp_f32_e32 v82, v82
	v_rcp_f32_e32 v80, v80
	v_add_f32_e32 v83, 1.0, v84
	v_rcp_f32_e32 v83, v83
	v_add_f32_e32 v82, 1.0, v82
	v_rcp_f32_e32 v82, v82
	v_mul_f32_e32 v80, v87, v80
	v_pk_mul_f32 v[74:75], v[74:75], v[210:211] op_sel_hi:[1,0]
	v_mul_f32_e32 v73, v73, v80
	v_mul_f32_e32 v80, v81, v83
	v_pk_mul_f32 v[70:71], v[70:71], v[210:211] op_sel_hi:[1,0]
	v_mul_f32_e32 v74, v74, v80
	v_mul_f32_e32 v80, v85, v82
	ds_bpermute_b32 v85, v173, v71
	ds_bpermute_b32 v86, v175, v71
	v_fma_f32 v88, v127, v71, v115
	v_pk_mul_f32 v[68:69], v[68:69], v[210:211] op_sel_hi:[1,0]
	ds_bpermute_b32 v82, v173, v69
	s_waitcnt lgkmcnt(2)
	v_cndmask_b32_e64 v85, v85, v107, s[46:47]
	s_waitcnt lgkmcnt(1)
	v_cndmask_b32_e32 v86, v86, v144, vcc
	v_fmac_f32_e32 v88, v123, v85
	v_fmac_f32_e32 v88, v119, v86
	v_mul_f32_e32 v85, 0xbfb8aa3b, v88
	v_exp_f32_e32 v85, v85
	ds_bpermute_b32 v84, v173, v70
	ds_bpermute_b32 v87, v175, v70
	ds_bpermute_b32 v83, v175, v69
	v_add_f32_e32 v85, 1.0, v85
	v_rcp_f32_e32 v85, v85
	v_mul_f32_e32 v75, v75, v80
	ds_bpermute_b32 v80, v173, v68
	ds_bpermute_b32 v81, v175, v68
	v_pk_mul_f32 v[66:67], v[66:67], v[210:211] op_sel_hi:[1,0]
	v_mul_f32_e32 v85, v88, v85
	s_waitcnt lgkmcnt(5)
	v_cndmask_b32_e64 v82, v82, v94, s[46:47]
	s_waitcnt lgkmcnt(4)
	v_cndmask_b32_e64 v84, v84, v106, s[46:47]
	s_waitcnt lgkmcnt(3)
	v_cndmask_b32_e32 v86, v87, v145, vcc
	v_fma_f32 v87, v126, v70, v114
	v_mul_f32_e32 v67, v67, v85
	v_fma_f32 v85, v125, v69, v113
	v_fmac_f32_e32 v87, v122, v84
	s_waitcnt lgkmcnt(2)
	v_cndmask_b32_e32 v83, v83, v95, vcc
	v_fmac_f32_e32 v85, v121, v82
	s_waitcnt lgkmcnt(1)
	v_cndmask_b32_e64 v80, v80, v92, s[46:47]
	v_fmac_f32_e32 v87, v118, v86
	v_fmac_f32_e32 v85, v117, v83
	v_fma_f32 v83, v124, v68, v112
	s_waitcnt lgkmcnt(0)
	v_cndmask_b32_e32 v81, v81, v93, vcc
	v_mul_f32_e32 v84, 0xbfb8aa3b, v87
	v_fmac_f32_e32 v83, v120, v80
	v_exp_f32_e32 v84, v84
	v_mul_f32_e32 v82, 0xbfb8aa3b, v85
	v_fmac_f32_e32 v83, v116, v81
	v_exp_f32_e32 v82, v82
	v_mul_f32_e32 v80, 0xbfb8aa3b, v83
	v_exp_f32_e32 v80, v80
	v_add_f32_e32 v84, 1.0, v84
	v_rcp_f32_e32 v84, v84
	v_add_f32_e32 v82, 1.0, v82
	v_rcp_f32_e32 v82, v82
	v_add_f32_e32 v80, 1.0, v80
	v_rcp_f32_e32 v80, v80
	v_mul_f32_e32 v81, v87, v84
	v_pk_mul_f32 v[64:65], v[64:65], v[210:211] op_sel_hi:[1,0]
	v_mul_f32_e32 v81, v66, v81
	v_mul_f32_e32 v66, v85, v82
	v_mul_f32_e32 v66, v65, v66
	v_mul_f32_e32 v65, v83, v80
	v_mul_f32_e32 v80, v64, v65
	v_cvt_pk_bf16_f32 v64, v72, v73
	v_mad_i64_i32 v[72:73], s[6:7], v196, s25, v[96:97]
	v_cmp_lt_u32_e64 s[44:45], 13, v176
	v_lshl_add_u64 v[148:149], v[176:177], 0, -12
	v_lshl_add_u64 v[72:73], v[72:73], 0, v[150:151]
	v_cvt_pk_bf16_f32 v65, v74, v75
	v_cvt_pk_bf16_f32 v66, v80, v66
	v_cvt_pk_bf16_f32 v67, v81, v67
	global_store_dwordx4 v[72:73], v[64:67], off
	s_and_saveexec_b64 s[6:7], s[44:45]
	s_cbranch_execz .LBB0_779
	v_lshl_add_u64 v[72:73], v[148:149], 0, s[0:1]
	v_cvt_pk_bf16_f32 v64, v76, v77
	v_cvt_pk_bf16_f32 v65, v78, v79
	v_cvt_pk_bf16_f32 v66, v68, v69
	v_mov_b64_e32 v[68:69], s[54:55]
	v_mad_u64_u32 v[68:69], s[0:1], v72, s25, v[68:69]
	v_mad_i32_i24 v69, v73, s25, v69
	v_lshl_add_u64 v[68:69], v[192:193], 1, v[68:69]
	v_cvt_pk_bf16_f32 v67, v70, v71
	global_store_dwordx4 v[68:69], v[64:67], off
